# as S12 with the per-tile workgroup barrier moved ahead of the last P.V MFMA block so the next tile's K-fragment LDS reads issue under those MFMAs
# speedup vs baseline: 1.0043x; 1.0014x over previous
; __device__ __forceinline__ void finishSM(f32x16& p0, f32x16& p1, float alpha, float& l_reg, bf16x8& pa0, bf16x8& pa1, bf16x8& pa2, bf16x8& pa3) {
;   for (int r = 0; r < 16; ++r) p1[r] = __builtin_amdgcn_exp2f(p1[r]);
;   float ps = 0; for (int r = 0; r < 16; ++r) ps += p0[r]; for (int r = 0; r < 16; ++r) ps += p1[r];
;   { auto rr = __builtin_amdgcn_permlane32_swap(__float_as_uint(ps), __float_as_uint(ps), false, false);
;     ps = __uint_as_float(rr[0]) + __uint_as_float(rr[1]); }
;   l_reg = l_reg * alpha + ps;
;     ...
;   PK4(p0, 0, pa0); PK4(p0, 8, pa1); PK4(p1, 0, pa2); PK4(p1, 8, pa3);
;     ...
; }
; __device__ __forceinline__ void kload(bf16x8 (&kf)[8], const char* Ks, int r32, int hi, int sb) {
; #pragma unroll
;   for (int d0 = 0; d0 < 4; ++d0) { const int cb = sb + (d0 * 16 + hi * 8) * 2;
;     kf[2 * d0] = *reinterpret_cast<const bf16x8*>(Ks + KSWZ(r32, cb)); kf[2 * d0 + 1] = *reinterpret_cast<const bf16x8*>(Ks + KSWZ(32 + r32, cb)); }
; }
; __device__ __forceinline__ void kmma(f32x16& p0, f32x16& p1, const bf16x8 (&kf)[8], const bf16x8* qr) {
;   asm volatile("s_waitcnt lgkmcnt(0)" ::: "memory"); SBAR();
;   p0 = f32x16{}; p1 = f32x16{};
; #pragma unroll
;   for (int d0 = 0; d0 < 4; ++d0) { p0 = __builtin_amdgcn_mfma_f32_32x32x16_bf16(kf[2 * d0], qr[d0], p0, 0, 0, 0); p1 = __builtin_amdgcn_mfma_f32_32x32x16_bf16(kf[2 * d0 + 1], qr[d0], p1, 0, 0, 0); }
; }
; __device__ __forceinline__ void qkt(f32x16& p0, f32x16& p1, const char* Ks, const bf16x8* qr, int r32, int hi, int sb) {
;   bf16x8 kf[8]; kload(kf, Ks, r32, hi, sb); SBAR(); kmma(p0, p1, kf, qr);
; }
; __device__ __forceinline__ int v_st(int k, int c) { const int kk = (k & ~0xC) | ((k & 4) << 1) | ((k & 8) >> 1); return ((kk >> 3) * 4 + (c >> 5)) * 512 + ((kk & 7) * 32 + (c & 31)) * 2; }
; __device__ __forceinline__ int v_rd_base(int lane) { return ((lane & 3) << 3) | (((lane >> 2) & 3) << 6) | (((lane >> 4) & 1) << 5) | (((lane >> 5) & 1) << 8); }
; template <int OFF> __device__ __forceinline__ s16x4 tr_read(int vb) {
;   s16x4 r; asm volatile("ds_read_b64_tr_b16 %0, %1 offset:%2" : "=&v"(r) : "v"(vb), "i"(OFF) : "memory"); return r;
; }
; template <int D0> __device__ __forceinline__ void v_frag_read(VFrag& f, int vb) {
;   f.l0 = tr_read<v_rd_off(D0, 0, 0)>(vb); f.h0 = tr_read<v_rd_off(D0, 0, 1)>(vb); f.l1 = tr_read<v_rd_off(D0, 1, 0)>(vb); f.h1 = tr_read<v_rd_off(D0, 1, 1)>(vb);
.LBB0_770:
	ds_read_b128 v[82:85], v245
	ds_read_b128 v[86:89], v245 offset:8192
	ds_read_b128 v[130:133], v246
	ds_read_b128 v[134:137], v246 offset:8192
	ds_read_b128 v[206:209], v247
	ds_read_b128 v[210:213], v247 offset:8192
	ds_read_b128 v[214:217], v255
	ds_read_b128 v[218:221], v255 offset:8192
	v_exp_f32_e32 v148, v66
	v_add_f32_e32 v66, 0, v175
	v_add_f32_e32 v66, v177, v66
	v_add_f32_e32 v66, v192, v66
	v_add_f32_e32 v66, v195, v66
	v_add_f32_e32 v66, v196, v66
	v_add_f32_e32 v66, v199, v66
	v_add_f32_e32 v66, v200, v66
	v_add_f32_e32 v66, v203, v66
	v_add_f32_e32 v66, v176, v66
	v_add_f32_e32 v66, v193, v66
	v_add_f32_e32 v66, v194, v66
	v_add_f32_e32 v66, v197, v66
	v_add_f32_e32 v66, v198, v66
	v_exp_f32_e32 v149, v67
	v_add_f32_e32 v66, v201, v66
	s_waitcnt lgkmcnt(7)
	v_mfma_f32_32x32x16_bf16 v[98:113], v[82:85], v[126:129], 0
	v_exp_f32_e32 v150, v68
	s_and_b32 s13, s36, 0xc000
	v_add_f32_e32 v66, v202, v66
	v_add_u32_e32 v244, s13, v164
	v_exp_f32_e32 v151, v69
	ds_read_b64_tr_b16 v[228:229], v244 offset:0
	v_add_f32_e32 v66, v204, v66
	ds_read_b64_tr_b16 v[230:231], v244 offset:0x800
	ds_read_b64_tr_b16 v[232:233], v244 offset:0x1000
	ds_read_b64_tr_b16 v[234:235], v244 offset:0x1800
	s_waitcnt lgkmcnt(10)
	v_mfma_f32_32x32x16_bf16 v[82:97], v[86:89], v[126:129], 0
	v_exp_f32_e32 v186, v70
	ds_read_b64_tr_b16 v[236:237], v244 offset:0x2000
	v_add_f32_e32 v66, v148, v66
	ds_read_b64_tr_b16 v[238:239], v244 offset:0x2800
	v_exp_f32_e32 v187, v71
	ds_read_b64_tr_b16 v[240:241], v244 offset:0x3000
	v_add_f32_e32 v66, v149, v66
	ds_read_b64_tr_b16 v[242:243], v244 offset:0x3800
	v_exp_f32_e32 v188, v72
	s_add_i32 s37, s12, 2
	s_cmpk_lt_u32 s12, 0x7e
	s_cselect_b64 s[0:1], -1, 0
	s_waitcnt lgkmcnt(13)
	v_mfma_f32_32x32x16_bf16 v[98:113], v[130:133], v[122:125], v[98:113]
	v_add_f32_e32 v66, v150, v66
	s_and_b64 s[10:11], s[0:1], exec
	v_exp_f32_e32 v189, v73
	s_cselect_b32 s10, 0, 0xffffff80
	v_add_f32_e32 v66, v151, v66
	s_add_i32 s58, s37, s10
	v_exp_f32_e32 v205, v74
	s_and_b64 s[0:1], s[0:1], exec
	s_cselect_b32 s1, s9, s30
	s_cselect_b32 s0, s8, s26
	s_lshl_b64 s[10:11], s[58:59], 17
	s_waitcnt lgkmcnt(12)
	v_mfma_f32_32x32x16_bf16 v[82:97], v[134:137], v[122:125], v[82:97]
	v_add_f32_e32 v66, v186, v66
	s_lshl_b64 s[0:1], s[0:1], 11
	v_exp_f32_e32 v222, v75
	s_add_u32 s10, s10, s0
	v_add_f32_e32 v66, v187, v66
	s_addc_u32 s11, s11, s1
	v_exp_f32_e32 v223, v76
	s_add_u32 s0, s20, s10
	v_add_f32_e32 v66, v188, v66
	s_addc_u32 s1, s21, s11
	s_add_u32 s10, s22, s10
	s_addc_u32 s11, s23, s11
	s_waitcnt lgkmcnt(11)
	v_mfma_f32_32x32x16_bf16 v[98:113], v[206:209], v[118:121], v[98:113]
	v_exp_f32_e32 v224, v77
	s_and_b32 s13, s37, 0xff
	v_add_f32_e32 v66, v189, v66
	s_mulk_i32 s13, 0xab
	v_exp_f32_e32 v225, v78
	s_lshr_b32 s13, s13, 9
	v_add_f32_e32 v66, v205, v66
	s_mul_i32 s13, s13, 3
	s_sub_i32 s13, s37, s13
	s_and_b32 s13, s13, 0xff
	s_waitcnt lgkmcnt(10)
	v_mfma_f32_32x32x16_bf16 v[82:97], v[210:213], v[118:121], v[82:97]
	v_exp_f32_e32 v226, v79
	s_lshl_b32 s13, s13, 14
	s_mov_b32 s100, s13
	v_add_f32_e32 v66, v222, v66
	s_add_i32 s42, s36, 0xffffc000
	v_exp_f32_e32 v227, v80
	s_and_b32 s42, s42, 0xc000
	v_add_f32_e32 v66, v223, v66
	s_add_i32 s13, s13, s27
	v_exp_f32_e32 v81, v81
	s_add_i32 s42, s42, s31
	v_lshl_add_u64 v[246:247], s[0:1], 0, v[146:147]
	s_mov_b32 m0, s13
	s_waitcnt lgkmcnt(9)
	v_mfma_f32_32x32x16_bf16 v[98:113], v[214:217], v[114:117], v[98:113]
	v_add_f32_e32 v66, v224, v66
	s_nop 0
	v_add_f32_e32 v66, v225, v66
	global_load_lds_dwordx4 v[246:247], off
	v_add_f32_e32 v66, v226, v66
	v_lshl_add_u64 v[246:247], s[10:11], 0, v[142:143]
	v_add_f32_e32 v66, v227, v66
	s_mov_b32 m0, s42
	s_nop 0
	global_load_lds_dwordx4 v[246:247], off
	v_lshl_add_u64 v[246:247], s[0:1], 0, v[144:145]
	s_waitcnt lgkmcnt(8)
	v_mfma_f32_32x32x16_bf16 v[82:97], v[218:221], v[114:117], v[82:97]
	v_add_f32_e32 v130, v81, v66
	s_add_i32 m0, s13, 0x2000
	v_mov_b32_e32 v131, v130
	s_nop 0
	v_cvt_pk_bf16_f32 v66, v175, v177
	global_load_lds_dwordx4 v[246:247], off
	v_cvt_pk_bf16_f32 v67, v192, v195
	v_lshl_add_u64 v[246:247], s[10:11], 0, v[154:155]
	v_cvt_pk_bf16_f32 v68, v196, v199
	s_add_i32 m0, s42, 0x2000
	s_nop 0
	global_load_lds_dwordx4 v[246:247], off
	v_permlane32_swap_b32_e32 v130, v131
	v_cvt_pk_bf16_f32 v69, v200, v203
	v_permlane32_swap_b32_e32 v66, v68
	v_cvt_pk_bf16_f32 v70, v176, v193
	v_cvt_pk_bf16_f32 v71, v194, v197
	v_cvt_pk_bf16_f32 v72, v198, v201
	v_cvt_pk_bf16_f32 v73, v202, v204
	v_cvt_pk_bf16_f32 v74, v148, v149
	v_cvt_pk_bf16_f32 v75, v150, v151
	v_cvt_pk_bf16_f32 v76, v186, v187
	v_cvt_pk_bf16_f32 v77, v188, v189
	v_cvt_pk_bf16_f32 v78, v205, v222
	v_cvt_pk_bf16_f32 v79, v223, v224
	v_cvt_pk_bf16_f32 v80, v225, v226
	v_cvt_pk_bf16_f32 v81, v227, v81
	v_permlane32_swap_b32_e32 v67, v69
	v_permlane32_swap_b32_e32 v70, v72
	v_permlane32_swap_b32_e32 v71, v73
	v_permlane32_swap_b32_e32 v74, v76
	v_permlane32_swap_b32_e32 v75, v77
	v_permlane32_swap_b32_e32 v78, v80
	v_permlane32_swap_b32_e32 v79, v81
	ds_read_b64_tr_b16 v[204:205], v244 offset:0x200
	ds_read_b64_tr_b16 v[206:207], v244 offset:0xa00
	ds_read_b64_tr_b16 v[208:209], v244 offset:0x1200
	ds_read_b64_tr_b16 v[210:211], v244 offset:0x1a00
	ds_read_b64_tr_b16 v[212:213], v244 offset:0x2200
	ds_read_b64_tr_b16 v[214:215], v244 offset:0x2a00
	ds_read_b64_tr_b16 v[216:217], v244 offset:0x3200
	ds_read_b64_tr_b16 v[218:219], v244 offset:0x3a00
	s_waitcnt lgkmcnt(14)
	v_mfma_f32_32x32x16_bf16 v[18:33], v[66:69], v[228:231], v[18:33]
	v_max_f32_e32 v245, v99, v99
	v_max_f32_e32 v246, v98, v98
	v_max_f32_e32 v245, v246, v245
	v_max3_f32 v245, v245, v100, v101
	v_max3_f32 v245, v245, v102, v103
	v_max3_f32 v245, v245, v104, v105
	v_max3_f32 v245, v245, v106, v107
	v_max3_f32 v245, v245, v108, v109
	s_waitcnt lgkmcnt(12)
; #define SBAR() __builtin_amdgcn_sched_barrier(0)
; __device__ __forceinline__ void pv_d0(f32x16* o, int vb, bf16x8 pa0, bf16x8 pa1, bf16x8 pa2, bf16x8 pa3) {
;   VFrag fa, fb;
;   v_frag_read<0>(fa, vb);
;   asm volatile("s_waitcnt lgkmcnt(0)" ::: "memory"); SBAR();
;   v_frag_read<1>(fb, vb); SBAR();
;   pv_mma(o[0], fa, pa0, pa1, pa2, pa3); SBAR();
;   asm volatile("s_waitcnt lgkmcnt(0)" ::: "memory"); SBAR();
;   v_frag_read<2>(fa, vb); SBAR();
;   pv_mma(o[1], fb, pa0, pa1, pa2, pa3); SBAR();
;   asm volatile("s_waitcnt lgkmcnt(0)" ::: "memory"); SBAR();
;   v_frag_read<3>(fb, vb); SBAR();
;   pv_mma(o[2], fa, pa0, pa1, pa2, pa3); SBAR();
;   asm volatile("s_waitcnt lgkmcnt(0)" ::: "memory"); SBAR();
;   pv_mma(o[3], fb, pa0, pa1, pa2, pa3);
; }
	v_mfma_f32_32x32x16_bf16 v[18:33], v[70:73], v[232:235], v[18:33]
	v_max3_f32 v245, v245, v110, v111
	v_max3_f32 v245, v245, v112, v113
	v_max3_f32 v245, v245, v82, v83
	v_max3_f32 v245, v245, v84, v85
	v_max3_f32 v245, v245, v86, v87
	v_max3_f32 v245, v245, v88, v89
	v_max3_f32 v245, v245, v90, v91
	v_max3_f32 v245, v245, v92, v93
	s_waitcnt lgkmcnt(10)
	v_mfma_f32_32x32x16_bf16 v[18:33], v[74:77], v[236:239], v[18:33]
	v_max3_f32 v245, v245, v94, v95
	v_max3_f32 v245, v245, v96, v97
	v_mov_b32_e32 v246, v245
	s_nop 1
	v_permlane32_swap_b32_e32 v245, v246
	v_max_f32_e32 v246, v246, v246
	v_max_f32_e32 v245, v245, v245
	v_max_f32_e32 v245, v245, v246
	v_sub_f32_e32 v246, v245, v174
	s_waitcnt lgkmcnt(8)
	v_mfma_f32_32x32x16_bf16 v[18:33], v[78:81], v[240:243], v[18:33]
	v_cmp_ge_f32_e32 vcc, s63, v246
	v_max_f32_e32 v246, v174, v174
	v_max_f32_e32 v245, v246, v245
	v_sub_f32_e32 v246, v174, v245
	v_mul_f32_e32 v246, 0x3e38aa3b, v246
	v_exp_f32_e32 v246, v246
	s_cmp_eq_u64 vcc, exec
	s_cselect_b64 s[0:1], -1, 0
	v_cndmask_b32_e64 v132, v246, 1.0, s[0:1]
	ds_read_b64_tr_b16 v[228:229], v244 offset:0x400
	ds_read_b64_tr_b16 v[230:231], v244 offset:0xc00
	ds_read_b64_tr_b16 v[232:233], v244 offset:0x1400
	ds_read_b64_tr_b16 v[234:235], v244 offset:0x1c00
	ds_read_b64_tr_b16 v[236:237], v244 offset:0x2400
	ds_read_b64_tr_b16 v[238:239], v244 offset:0x2c00
	ds_read_b64_tr_b16 v[240:241], v244 offset:0x3400
	ds_read_b64_tr_b16 v[242:243], v244 offset:0x3c00
	v_cndmask_b32_e64 v133, v245, v174, s[0:1]
	v_mul_f32_e32 v148, 0xbe38aa3b, v133
	s_waitcnt lgkmcnt(14)
	v_mfma_f32_32x32x16_bf16 v[50:65], v[66:69], v[204:207], v[50:65]
	v_fmamk_f32 v98, v98, 0x3e38aa3b, v148
	v_fmamk_f32 v99, v99, 0x3e38aa3b, v148
	v_fmamk_f32 v100, v100, 0x3e38aa3b, v148
	v_fmamk_f32 v101, v101, 0x3e38aa3b, v148
	s_waitcnt lgkmcnt(12)
	v_mfma_f32_32x32x16_bf16 v[50:65], v[70:73], v[208:211], v[50:65]
	v_fmamk_f32 v102, v102, 0x3e38aa3b, v148
	v_fmamk_f32 v103, v103, 0x3e38aa3b, v148
	v_fmamk_f32 v104, v104, 0x3e38aa3b, v148
	v_fmamk_f32 v105, v105, 0x3e38aa3b, v148
	s_waitcnt lgkmcnt(10)
	v_mfma_f32_32x32x16_bf16 v[50:65], v[74:77], v[212:215], v[50:65]
	v_fmamk_f32 v106, v106, 0x3e38aa3b, v148
	v_fmamk_f32 v107, v107, 0x3e38aa3b, v148
	v_fmamk_f32 v108, v108, 0x3e38aa3b, v148
	v_fmamk_f32 v109, v109, 0x3e38aa3b, v148
	s_waitcnt lgkmcnt(8)
	v_mfma_f32_32x32x16_bf16 v[50:65], v[78:81], v[216:219], v[50:65]
	v_fmamk_f32 v110, v110, 0x3e38aa3b, v148
	v_fmamk_f32 v111, v111, 0x3e38aa3b, v148
	v_fmamk_f32 v112, v112, 0x3e38aa3b, v148
	v_fmamk_f32 v113, v113, 0x3e38aa3b, v148
	ds_read_b64_tr_b16 v[204:205], v244 offset:0x600
	ds_read_b64_tr_b16 v[206:207], v244 offset:0xe00
	ds_read_b64_tr_b16 v[208:209], v244 offset:0x1600
	ds_read_b64_tr_b16 v[210:211], v244 offset:0x1e00
	ds_read_b64_tr_b16 v[212:213], v244 offset:0x2600
	ds_read_b64_tr_b16 v[214:215], v244 offset:0x2e00
	ds_read_b64_tr_b16 v[216:217], v244 offset:0x3600
	ds_read_b64_tr_b16 v[218:219], v244 offset:0x3e00
	s_waitcnt lgkmcnt(14)
	v_mfma_f32_32x32x16_bf16 v[34:49], v[66:69], v[228:231], v[34:49]
	v_fmamk_f32 v82, v82, 0x3e38aa3b, v148
	v_fmamk_f32 v83, v83, 0x3e38aa3b, v148
	v_fmamk_f32 v84, v84, 0x3e38aa3b, v148
	v_fmamk_f32 v85, v85, 0x3e38aa3b, v148
	s_waitcnt lgkmcnt(12)
	v_mfma_f32_32x32x16_bf16 v[34:49], v[70:73], v[232:235], v[34:49]
	v_fmamk_f32 v86, v86, 0x3e38aa3b, v148
	v_fmamk_f32 v87, v87, 0x3e38aa3b, v148
	s_add_i32 s13, s36, 0xffff4000
	v_fmamk_f32 v149, v88, 0x3e38aa3b, v148
	s_waitcnt lgkmcnt(10)
	v_mfma_f32_32x32x16_bf16 v[34:49], v[74:77], v[236:239], v[34:49]
	v_fmamk_f32 v150, v89, 0x3e38aa3b, v148
	v_fmamk_f32 v151, v90, 0x3e38aa3b, v148
	v_fmamk_f32 v186, v91, 0x3e38aa3b, v148
	v_fmamk_f32 v187, v92, 0x3e38aa3b, v148
	s_waitcnt lgkmcnt(8)
	v_mfma_f32_32x32x16_bf16 v[34:49], v[78:81], v[240:243], v[34:49]
	v_fmamk_f32 v188, v93, 0x3e38aa3b, v148
	v_fmamk_f32 v189, v94, 0x3e38aa3b, v148
	v_exp_f32_e32 v192, v98
	v_exp_f32_e32 v193, v99
	v_exp_f32_e32 v194, v100
	v_exp_f32_e32 v195, v101
	s_waitcnt vmcnt(4)
	s_waitcnt lgkmcnt(0)
	s_barrier
	v_mfma_f32_32x32x16_bf16 v[2:17], v[66:69], v[204:207], v[2:17]
	v_exp_f32_e32 v196, v102
	v_exp_f32_e32 v197, v103
	v_exp_f32_e32 v198, v104
	v_exp_f32_e32 v199, v105
	v_mfma_f32_32x32x16_bf16 v[2:17], v[70:73], v[208:211], v[2:17]
	v_exp_f32_e32 v200, v106
	v_exp_f32_e32 v201, v107
	v_exp_f32_e32 v202, v108
	v_exp_f32_e32 v203, v109
	v_exp_f32_e32 v204, v110
	v_exp_f32_e32 v205, v111
	v_mfma_f32_32x32x16_bf16 v[2:17], v[74:77], v[212:215], v[2:17]
	v_exp_f32_e32 v206, v112
	v_exp_f32_e32 v207, v113
	v_fmamk_f32 v208, v95, 0x3e38aa3b, v148
	v_fmamk_f32 v209, v96, 0x3e38aa3b, v148
	v_fmac_f32_e32 v148, 0x3e38aa3b, v97
	v_mfma_f32_32x32x16_bf16 v[2:17], v[78:81], v[216:219], v[2:17]
	v_add_u32_e32 v245, s101, v169
	v_add_u32_e32 v246, s101, v170
	v_add_u32_e32 v247, s101, v171
	v_add_u32_e32 v244, s101, v172
	v_cmp_gt_f32_e32 vcc, 1.0, v132
	s_cbranch_vccz .LBB0_774
	s_and_saveexec_b64 s[10:11], s[40:41]
	ds_write_b32 v162, v132 offset:128
	s_or_b64 exec, exec, s[10:11]
	s_waitcnt lgkmcnt(0)
	v_add_u32_e32 v67, s18, v140
	ds_read_b128 v[68:71], v67 offset:224
	ds_read_b128 v[72:75], v67 offset:192
	ds_read_b128 v[76:79], v67 offset:160
	ds_read_b128 v[134:137], v67 offset:128
	s_waitcnt lgkmcnt(0)
	v_pk_mul_f32 v[30:31], v[30:31], v[68:69]
	v_pk_mul_f32 v[26:27], v[26:27], v[72:73]
	v_pk_mul_f32 v[22:23], v[22:23], v[76:77]
	v_pk_mul_f32 v[32:33], v[32:33], v[70:71]
	v_pk_mul_f32 v[28:29], v[28:29], v[74:75]
	v_pk_mul_f32 v[24:25], v[24:25], v[78:79]
	v_pk_mul_f32 v[20:21], v[20:21], v[136:137]
	v_pk_mul_f32 v[18:19], v[18:19], v[134:135]
	v_pk_mul_f32 v[62:63], v[62:63], v[68:69]
	v_pk_mul_f32 v[58:59], v[58:59], v[72:73]
	v_pk_mul_f32 v[54:55], v[54:55], v[76:77]
	v_pk_mul_f32 v[64:65], v[64:65], v[70:71]
	v_pk_mul_f32 v[60:61], v[60:61], v[74:75]
	v_pk_mul_f32 v[56:57], v[56:57], v[78:79]
	v_pk_mul_f32 v[52:53], v[52:53], v[136:137]
	v_pk_mul_f32 v[50:51], v[50:51], v[134:135]
	v_pk_mul_f32 v[46:47], v[46:47], v[68:69]
	v_pk_mul_f32 v[42:43], v[42:43], v[72:73]
	v_pk_mul_f32 v[38:39], v[38:39], v[76:77]
	v_pk_mul_f32 v[48:49], v[48:49], v[70:71]
	v_pk_mul_f32 v[44:45], v[44:45], v[74:75]
	v_pk_mul_f32 v[40:41], v[40:41], v[78:79]
	v_pk_mul_f32 v[36:37], v[36:37], v[136:137]
	v_pk_mul_f32 v[34:35], v[34:35], v[134:135]
	v_pk_mul_f32 v[14:15], v[14:15], v[68:69]
	v_pk_mul_f32 v[10:11], v[10:11], v[72:73]
	v_pk_mul_f32 v[6:7], v[6:7], v[76:77]
	v_pk_mul_f32 v[16:17], v[16:17], v[70:71]
	v_pk_mul_f32 v[12:13], v[12:13], v[74:75]
	v_pk_mul_f32 v[8:9], v[8:9], v[78:79]
	v_pk_mul_f32 v[4:5], v[4:5], v[136:137]
	v_pk_mul_f32 v[2:3], v[2:3], v[134:135]
; #define SBAR() __builtin_amdgcn_sched_barrier(0)
; __device__ __forceinline__ void kload(bf16x8 (&kf)[8], const char* Ks, int r32, int hi, int sb) {
; #pragma unroll
;   for (int d0 = 0; d0 < 4; ++d0) { const int cb = sb + (d0 * 16 + hi * 8) * 2;
;     kf[2 * d0] = *reinterpret_cast<const bf16x8*>(Ks + KSWZ(r32, cb)); kf[2 * d0 + 1] = *reinterpret_cast<const bf16x8*>(Ks + KSWZ(32 + r32, cb)); }
; }
; __device__ __forceinline__ void kmma(f32x16& p0, f32x16& p1, const bf16x8 (&kf)[8], const bf16x8* qr) {
;   asm volatile("s_waitcnt lgkmcnt(0)" ::: "memory"); SBAR();
;   p0 = f32x16{}; p1 = f32x16{};
; #pragma unroll
;   for (int d0 = 0; d0 < 4; ++d0) { p0 = __builtin_amdgcn_mfma_f32_32x32x16_bf16(kf[2 * d0], qr[d0], p0, 0, 0, 0); p1 = __builtin_amdgcn_mfma_f32_32x32x16_bf16(kf[2 * d0 + 1], qr[d0], p1, 0, 0, 0); }
; }
; __device__ __forceinline__ void qkt(f32x16& p0, f32x16& p1, const char* Ks, const bf16x8* qr, int r32, int hi, int sb) {
;   bf16x8 kf[8]; kload(kf, Ks, r32, hi, sb); SBAR(); kmma(p0, p1, kf, qr);
.LBB0_774:
	ds_read_b128 v[66:69], v245
	ds_read_b128 v[70:73], v245 offset:8192
	ds_read_b128 v[98:101], v246
	ds_read_b128 v[102:105], v246 offset:8192
	ds_read_b128 v[106:109], v247
	ds_read_b128 v[110:113], v247 offset:8192
	ds_read_b128 v[134:137], v244
	ds_read_b128 v[174:177], v244 offset:8192
	v_exp_f32_e32 v210, v82
	v_exp_f32_e32 v211, v83
	v_exp_f32_e32 v212, v84
	v_exp_f32_e32 v213, v85
	v_exp_f32_e32 v214, v86
	v_exp_f32_e32 v215, v87
	v_add_f32_e32 v216, 0, v192
	v_add_f32_e32 v216, v193, v216
	v_add_f32_e32 v216, v194, v216
	v_add_f32_e32 v216, v195, v216
	v_exp_f32_e32 v149, v149
	v_exp_f32_e32 v150, v150
	v_exp_f32_e32 v151, v151
	v_exp_f32_e32 v186, v186
	v_exp_f32_e32 v187, v187
	v_exp_f32_e32 v188, v188
	s_waitcnt lgkmcnt(7)
	v_mfma_f32_32x32x16_bf16 v[82:97], v[66:69], v[126:129], 0
	v_exp_f32_e32 v189, v189
	s_and_b32 s46, s13, 0xc000
	v_exp_f32_e32 v208, v208
	v_add_u32_e32 v244, s46, v164
	v_exp_f32_e32 v209, v209
	ds_read_b64_tr_b16 v[228:229], v244 offset:0
	v_exp_f32_e32 v148, v148
	ds_read_b64_tr_b16 v[230:231], v244 offset:0x800
	ds_read_b64_tr_b16 v[232:233], v244 offset:0x1000
	s_waitcnt lgkmcnt(9)
	v_mfma_f32_32x32x16_bf16 v[66:81], v[70:73], v[126:129], 0
	v_add_f32_e32 v255, v196, v216
	ds_read_b64_tr_b16 v[234:235], v244 offset:0x1800
	v_add_f32_e32 v255, v197, v255
	ds_read_b64_tr_b16 v[236:237], v244 offset:0x2000
	v_add_f32_e32 v255, v198, v255
	ds_read_b64_tr_b16 v[238:239], v244 offset:0x2800
	v_add_f32_e32 v255, v199, v255
	ds_read_b64_tr_b16 v[240:241], v244 offset:0x3000
	v_add_f32_e32 v255, v200, v255
	ds_read_b64_tr_b16 v[242:243], v244 offset:0x3800
	s_waitcnt lgkmcnt(13)
	v_mfma_f32_32x32x16_bf16 v[82:97], v[98:101], v[122:125], v[82:97]
	v_add_f32_e32 v255, v201, v255
	s_add_i32 s46, s12, 3
	v_add_f32_e32 v255, v202, v255
	s_cmpk_lt_u32 s12, 0x7d
	v_add_f32_e32 v255, v203, v255
	s_cselect_b64 s[42:43], -1, 0
	v_add_f32_e32 v255, v204, v255
	s_and_b64 s[44:45], s[42:43], exec
	s_cselect_b32 s44, 0, 0xffffff80
	s_waitcnt lgkmcnt(12)
	v_mfma_f32_32x32x16_bf16 v[66:81], v[102:105], v[122:125], v[66:81]
	v_add_f32_e32 v255, v205, v255
	s_add_i32 s58, s46, s44
	v_add_f32_e32 v255, v206, v255
	s_and_b64 s[42:43], s[42:43], exec
	v_add_f32_e32 v255, v207, v255
	s_cselect_b32 s43, s9, s30
	v_add_f32_e32 v255, v210, v255
	s_cselect_b32 s42, s8, s26
	v_add_f32_e32 v255, v211, v255
	s_lshl_b64 s[44:45], s[58:59], 17
	s_waitcnt lgkmcnt(11)
	v_mfma_f32_32x32x16_bf16 v[82:97], v[106:109], v[118:121], v[82:97]
	v_add_f32_e32 v255, v212, v255
	s_lshl_b64 s[42:43], s[42:43], 11
	v_add_f32_e32 v255, v213, v255
	s_add_u32 s44, s44, s42
	v_add_f32_e32 v255, v214, v255
	s_addc_u32 s45, s45, s43
	v_add_f32_e32 v255, v215, v255
	s_add_u32 s42, s20, s44
	s_addc_u32 s43, s21, s45
	s_waitcnt lgkmcnt(10)
	v_mfma_f32_32x32x16_bf16 v[66:81], v[110:113], v[118:121], v[66:81]
	v_add_f32_e32 v255, v149, v255
	s_add_u32 s44, s22, s44
	v_add_f32_e32 v255, v150, v255
	s_mul_i32 s47, s46, 0xab
	v_add_f32_e32 v255, v151, v255
	s_addc_u32 s45, s23, s45
	v_add_f32_e32 v255, v186, v255
	s_bfe_u32 s47, s47, 0x70009
	v_add_f32_e32 v255, v187, v255
	s_mul_i32 s47, s47, 3
	s_waitcnt lgkmcnt(9)
	v_mfma_f32_32x32x16_bf16 v[82:97], v[134:137], v[114:117], v[82:97]
	v_add_f32_e32 v255, v188, v255
	s_sub_i32 s46, s46, s47
	v_add_f32_e32 v255, v189, v255
	s_and_b32 s46, s46, 0xff
	v_add_f32_e32 v255, v208, v255
	s_lshl_b32 s46, s46, 14
	s_mov_b32 s101, s46
	v_add_f32_e32 v255, v209, v255
	s_add_i32 s46, s46, s27
	v_add_f32_e32 v99, v148, v255
	s_and_b32 s47, s36, 0xc000
	s_add_i32 s47, s47, s31
	s_cmpk_gt_u32 s12, 0x80
	s_cselect_b64 s[10:11], -1, 0
	s_and_b64 vcc, exec, s[10:11]
	s_cbranch_vccnz .LBB0_776
	v_lshl_add_u64 v[246:247], s[42:43], 0, v[146:147]
	s_mov_b32 m0, s46
	s_nop 0
	global_load_lds_dwordx4 v[246:247], off
	v_lshl_add_u64 v[246:247], s[44:45], 0, v[142:143]
	s_mov_b32 m0, s47
	s_nop 0
	global_load_lds_dwordx4 v[246:247], off
	v_lshl_add_u64 v[246:247], s[42:43], 0, v[144:145]
	s_add_i32 m0, s46, 0x2000
	s_nop 0
	global_load_lds_dwordx4 v[246:247], off
	v_lshl_add_u64 v[246:247], s[44:45], 0, v[154:155]
	s_add_i32 m0, s47, 0x2000
	s_nop 0
	global_load_lds_dwordx4 v[246:247], off
; #define SBAR() __builtin_amdgcn_sched_barrier(0)
; __device__ __forceinline__ void partialSM(f32x16& p0, f32x16& p1, float& m_reg, float& mn, float& alpha) {
;   constexpr float C = SCALE * 1.4426950408889634f;
;   float pmax = p0[0]; for (int r = 1; r < 16; ++r) pmax = fmaxf(pmax, p0[r]); for (int r = 0; r < 16; ++r) pmax = fmaxf(pmax, p1[r]);
;   { auto rr = __builtin_amdgcn_permlane32_swap(__float_as_uint(pmax), __float_as_uint(pmax), false, false);
;     pmax = fmaxf(__uint_as_float(rr[0]), __uint_as_float(rr[1])); }
;   if (__builtin_expect(__all(pmax - m_reg <= THR / SCALE), 1)) { mn = m_reg; alpha = 1.f; }
;   else { mn = fmaxf(m_reg, pmax); alpha = __builtin_amdgcn_exp2f((m_reg - mn) * C); m_reg = mn; }
;   float mnC = -mn * C;
;   for (int r = 0; r < 16; ++r) p0[r] = fmaf(p0[r], C, mnC); for (int r = 0; r < 16; ++r) p1[r] = fmaf(p1[r], C, mnC);
;   for (int r = 0; r < 16; ++r) p0[r] = __builtin_amdgcn_exp2f(p0[r]);
; }
; __device__ __forceinline__ void finishSM(f32x16& p0, f32x16& p1, float alpha, float& l_reg, bf16x8& pa0, bf16x8& pa1, bf16x8& pa2, bf16x8& pa3) {
;   for (int r = 0; r < 16; ++r) p1[r] = __builtin_amdgcn_exp2f(p1[r]);
;   float ps = 0; for (int r = 0; r < 16; ++r) ps += p0[r]; for (int r = 0; r < 16; ++r) ps += p1[r];
;   { auto rr = __builtin_amdgcn_permlane32_swap(__float_as_uint(ps), __float_as_uint(ps), false, false);
;     ps = __uint_as_float(rr[0]) + __uint_as_float(rr[1]); }
;   l_reg = l_reg * alpha + ps;
;     ...
;   PK4(p0, 0, pa0); PK4(p0, 8, pa1); PK4(p1, 0, pa2); PK4(p1, 8, pa3);
;     ...
; }
; __device__ __forceinline__ void pv_d0(f32x16* o, int vb, bf16x8 pa0, bf16x8 pa1, bf16x8 pa2, bf16x8 pa3) {
;   VFrag fa, fb;
;   v_frag_read<0>(fa, vb);
;   asm volatile("s_waitcnt lgkmcnt(0)" ::: "memory"); SBAR();
;   v_frag_read<1>(fb, vb); SBAR();
;   pv_mma(o[0], fa, pa0, pa1, pa2, pa3); SBAR();
;   asm volatile("s_waitcnt lgkmcnt(0)" ::: "memory"); SBAR();
;   v_frag_read<2>(fa, vb); SBAR();
;   pv_mma(o[1], fb, pa0, pa1, pa2, pa3); SBAR();
;   asm volatile("s_waitcnt lgkmcnt(0)" ::: "memory"); SBAR();
;   v_frag_read<3>(fb, vb); SBAR();
;   pv_mma(o[2], fa, pa0, pa1, pa2, pa3); SBAR();
;   asm volatile("s_waitcnt lgkmcnt(0)" ::: "memory"); SBAR();
;   pv_mma(o[3], fb, pa0, pa1, pa2, pa3);
; }
.LBB0_776:
	v_mov_b32_e32 v100, v99
	s_nop 1
	v_permlane32_swap_b32_e32 v99, v100
	v_cvt_pk_bf16_f32 v102, v192, v193
	v_cvt_pk_bf16_f32 v103, v194, v195
	v_cvt_pk_bf16_f32 v104, v196, v197
	v_cvt_pk_bf16_f32 v105, v198, v199
	s_waitcnt lgkmcnt(8)
	v_mfma_f32_32x32x16_bf16 v[66:81], v[174:177], v[114:117], v[66:81]
	v_cvt_pk_bf16_f32 v106, v200, v201
	v_cvt_pk_bf16_f32 v107, v202, v203
	v_cvt_pk_bf16_f32 v108, v204, v205
	v_cvt_pk_bf16_f32 v109, v206, v207
	v_cvt_pk_bf16_f32 v110, v210, v211
	v_cvt_pk_bf16_f32 v111, v212, v213
	v_cvt_pk_bf16_f32 v112, v214, v215
	v_cvt_pk_bf16_f32 v113, v149, v150
	v_cvt_pk_bf16_f32 v134, v151, v186
	v_cvt_pk_bf16_f32 v135, v187, v188
	v_cvt_pk_bf16_f32 v136, v189, v208
	v_cvt_pk_bf16_f32 v137, v209, v148
	v_permlane32_swap_b32_e32 v102, v104
	v_permlane32_swap_b32_e32 v103, v105
	v_permlane32_swap_b32_e32 v106, v108
	v_permlane32_swap_b32_e32 v107, v109
	v_permlane32_swap_b32_e32 v110, v112
	v_permlane32_swap_b32_e32 v111, v113
	v_permlane32_swap_b32_e32 v134, v136
	v_permlane32_swap_b32_e32 v135, v137
	ds_read_b64_tr_b16 v[204:205], v244 offset:0x200
	ds_read_b64_tr_b16 v[206:207], v244 offset:0xa00
	ds_read_b64_tr_b16 v[208:209], v244 offset:0x1200
	ds_read_b64_tr_b16 v[210:211], v244 offset:0x1a00
	ds_read_b64_tr_b16 v[212:213], v244 offset:0x2200
	ds_read_b64_tr_b16 v[214:215], v244 offset:0x2a00
	ds_read_b64_tr_b16 v[216:217], v244 offset:0x3200
	ds_read_b64_tr_b16 v[218:219], v244 offset:0x3a00
	s_waitcnt lgkmcnt(14)
	v_mfma_f32_32x32x16_bf16 v[18:33], v[102:105], v[228:231], v[18:33]
	v_max_f32_e32 v245, v83, v83
	v_max_f32_e32 v246, v82, v82
	v_max_f32_e32 v245, v246, v245
	v_max3_f32 v245, v245, v84, v85
	v_max3_f32 v245, v245, v86, v87
	v_max3_f32 v245, v245, v88, v89
	v_max3_f32 v245, v245, v90, v91
	v_max3_f32 v245, v245, v92, v93
	s_waitcnt lgkmcnt(12)
	v_mfma_f32_32x32x16_bf16 v[18:33], v[106:109], v[232:235], v[18:33]
	v_max3_f32 v245, v245, v94, v95
	v_max3_f32 v245, v245, v96, v97
	v_max3_f32 v245, v245, v66, v67
	v_max3_f32 v245, v245, v68, v69
	v_max3_f32 v245, v245, v70, v71
	v_max3_f32 v245, v245, v72, v73
	v_max3_f32 v245, v245, v74, v75
	v_max3_f32 v245, v245, v76, v77
	s_waitcnt lgkmcnt(10)
	v_mfma_f32_32x32x16_bf16 v[18:33], v[110:113], v[236:239], v[18:33]
	v_max3_f32 v245, v245, v78, v79
	v_max3_f32 v245, v245, v80, v81
	v_mov_b32_e32 v246, v245
	s_nop 1
	v_permlane32_swap_b32_e32 v245, v246
	v_max_f32_e32 v246, v246, v246
	v_max_f32_e32 v245, v245, v245
	v_max_f32_e32 v245, v245, v246
	v_sub_f32_e32 v246, v245, v133
	s_waitcnt lgkmcnt(8)
	v_mfma_f32_32x32x16_bf16 v[18:33], v[134:137], v[240:243], v[18:33]
	v_cmp_ge_f32_e32 vcc, s63, v246
	v_max_f32_e32 v246, v133, v133
	v_max_f32_e32 v245, v246, v245
	v_sub_f32_e32 v246, v133, v245
	v_mul_f32_e32 v246, 0x3e38aa3b, v246
	v_exp_f32_e32 v246, v246
	s_cmp_eq_u64 vcc, exec
	s_cselect_b64 s[0:1], -1, 0
	v_cndmask_b32_e64 v247, v246, 1.0, s[0:1]
	ds_read_b64_tr_b16 v[228:229], v244 offset:0x400
	ds_read_b64_tr_b16 v[230:231], v244 offset:0xc00
	ds_read_b64_tr_b16 v[232:233], v244 offset:0x1400
	ds_read_b64_tr_b16 v[234:235], v244 offset:0x1c00
	ds_read_b64_tr_b16 v[236:237], v244 offset:0x2400
	ds_read_b64_tr_b16 v[238:239], v244 offset:0x2c00
	ds_read_b64_tr_b16 v[240:241], v244 offset:0x3400
	ds_read_b64_tr_b16 v[242:243], v244 offset:0x3c00
	v_cndmask_b32_e64 v174, v245, v133, s[0:1]
	v_mul_f32_e32 v98, 0xbe38aa3b, v174
	s_waitcnt lgkmcnt(14)
	v_mfma_f32_32x32x16_bf16 v[50:65], v[102:105], v[204:207], v[50:65]
	v_fmamk_f32 v82, v82, 0x3e38aa3b, v98
	v_fmamk_f32 v83, v83, 0x3e38aa3b, v98
	v_fmamk_f32 v84, v84, 0x3e38aa3b, v98
	v_fmamk_f32 v85, v85, 0x3e38aa3b, v98
	s_waitcnt lgkmcnt(12)
	v_mfma_f32_32x32x16_bf16 v[50:65], v[106:109], v[208:211], v[50:65]
	v_fmamk_f32 v86, v86, 0x3e38aa3b, v98
	v_fmamk_f32 v87, v87, 0x3e38aa3b, v98
	v_fmamk_f32 v88, v88, 0x3e38aa3b, v98
	v_fmamk_f32 v89, v89, 0x3e38aa3b, v98
	s_waitcnt lgkmcnt(10)
	v_mfma_f32_32x32x16_bf16 v[50:65], v[110:113], v[212:215], v[50:65]
	v_fmamk_f32 v90, v90, 0x3e38aa3b, v98
	v_fmamk_f32 v91, v91, 0x3e38aa3b, v98
	v_fmamk_f32 v92, v92, 0x3e38aa3b, v98
	v_fmamk_f32 v93, v93, 0x3e38aa3b, v98
	s_waitcnt lgkmcnt(8)
	v_mfma_f32_32x32x16_bf16 v[50:65], v[134:137], v[216:219], v[50:65]
	v_fmamk_f32 v94, v94, 0x3e38aa3b, v98
	v_fmamk_f32 v95, v95, 0x3e38aa3b, v98
	v_fmamk_f32 v96, v96, 0x3e38aa3b, v98
	v_fmamk_f32 v97, v97, 0x3e38aa3b, v98
	ds_read_b64_tr_b16 v[204:205], v244 offset:0x600
	ds_read_b64_tr_b16 v[206:207], v244 offset:0xe00
	ds_read_b64_tr_b16 v[208:209], v244 offset:0x1600
	ds_read_b64_tr_b16 v[210:211], v244 offset:0x1e00
	ds_read_b64_tr_b16 v[212:213], v244 offset:0x2600
	ds_read_b64_tr_b16 v[214:215], v244 offset:0x2e00
	ds_read_b64_tr_b16 v[216:217], v244 offset:0x3600
	ds_read_b64_tr_b16 v[218:219], v244 offset:0x3e00
	s_waitcnt lgkmcnt(14)
	v_mfma_f32_32x32x16_bf16 v[34:49], v[102:105], v[228:231], v[34:49]
	s_mov_b32 s46, 0x3e38aa3b
	v_pk_fma_f32 v[80:81], v[80:81], s[46:47], v[98:99] op_sel_hi:[1,0,0]
	v_pk_fma_f32 v[78:79], v[78:79], s[46:47], v[98:99] op_sel_hi:[1,0,0]
	s_waitcnt lgkmcnt(12)
	v_mfma_f32_32x32x16_bf16 v[34:49], v[106:109], v[232:235], v[34:49]
	v_pk_fma_f32 v[76:77], v[76:77], s[46:47], v[98:99] op_sel_hi:[1,0,0]
	v_pk_fma_f32 v[74:75], v[74:75], s[46:47], v[98:99] op_sel_hi:[1,0,0]
	v_pk_fma_f32 v[72:73], v[72:73], s[46:47], v[98:99] op_sel_hi:[1,0,0]
	s_waitcnt lgkmcnt(10)
	v_mfma_f32_32x32x16_bf16 v[34:49], v[110:113], v[236:239], v[34:49]
	v_pk_fma_f32 v[70:71], v[70:71], s[46:47], v[98:99] op_sel_hi:[1,0,0]
	v_pk_fma_f32 v[68:69], v[68:69], s[46:47], v[98:99] op_sel_hi:[1,0,0]
	v_pk_fma_f32 v[66:67], v[66:67], s[46:47], v[98:99] op_sel_hi:[1,0,0]
	s_waitcnt lgkmcnt(8)
	v_mfma_f32_32x32x16_bf16 v[34:49], v[134:137], v[240:243], v[34:49]
	v_exp_f32_e32 v175, v82
	v_exp_f32_e32 v177, v83
	v_exp_f32_e32 v192, v84
	s_waitcnt lgkmcnt(0)
	s_mov_b64 s[0:1], -1
	s_and_b64 vcc, exec, s[10:11]
	s_cbranch_vccz .LBB0_782
	s_waitcnt vmcnt(0)
	s_barrier
	s_mov_b64 s[0:1], 0

; #define SBAR() __builtin_amdgcn_sched_barrier(0)
; __device__ __forceinline__ void pv_d0(f32x16* o, int vb, bf16x8 pa0, bf16x8 pa1, bf16x8 pa2, bf16x8 pa3) {
;   VFrag fa, fb;
;   v_frag_read<0>(fa, vb);
;   asm volatile("s_waitcnt lgkmcnt(0)" ::: "memory"); SBAR();
;   v_frag_read<1>(fb, vb); SBAR();
;   pv_mma(o[0], fa, pa0, pa1, pa2, pa3); SBAR();
;   asm volatile("s_waitcnt lgkmcnt(0)" ::: "memory"); SBAR();
;   v_frag_read<2>(fa, vb); SBAR();
;   pv_mma(o[1], fb, pa0, pa1, pa2, pa3); SBAR();
;   asm volatile("s_waitcnt lgkmcnt(0)" ::: "memory"); SBAR();
;   v_frag_read<3>(fb, vb); SBAR();
;   pv_mma(o[2], fa, pa0, pa1, pa2, pa3); SBAR();
;   asm volatile("s_waitcnt lgkmcnt(0)" ::: "memory"); SBAR();
;   pv_mma(o[3], fb, pa0, pa1, pa2, pa3);
; }
.LBB0_784:
	v_mfma_f32_32x32x16_bf16 v[2:17], v[102:105], v[204:207], v[2:17]
	v_mov_b32_e32 v205, v247
	v_exp_f32_e32 v204, v97
	v_exp_f32_e32 v195, v85
	v_exp_f32_e32 v196, v86
	v_exp_f32_e32 v199, v87
	v_exp_f32_e32 v200, v88
	v_mfma_f32_32x32x16_bf16 v[2:17], v[106:109], v[208:211], v[2:17]
	v_exp_f32_e32 v203, v89
	v_exp_f32_e32 v176, v90
	v_exp_f32_e32 v193, v91
	v_exp_f32_e32 v194, v92
	v_mfma_f32_32x32x16_bf16 v[2:17], v[110:113], v[212:215], v[2:17]
	v_exp_f32_e32 v197, v93
	v_exp_f32_e32 v198, v94
	v_exp_f32_e32 v201, v95
	v_exp_f32_e32 v202, v96
	v_mfma_f32_32x32x16_bf16 v[2:17], v[134:137], v[216:219], v[2:17]
	v_add_u32_e32 v245, s100, v169
	v_add_u32_e32 v246, s100, v170
	v_add_u32_e32 v247, s100, v171
	v_add_u32_e32 v255, s100, v172
	v_cmp_gt_f32_e32 vcc, 1.0, v205
	s_cbranch_vccz .LBB0_780
	s_and_saveexec_b64 s[12:13], s[40:41]
	ds_write_b32 v162, v205 offset:128
	s_or_b64 exec, exec, s[12:13]
	s_waitcnt lgkmcnt(0)
	v_add_u32_e32 v101, s18, v140
	ds_read_b128 v[102:105], v101 offset:224
	ds_read_b128 v[106:109], v101 offset:192
	ds_read_b128 v[110:113], v101 offset:160
	ds_read_b128 v[134:137], v101 offset:128
	s_waitcnt lgkmcnt(0)
	v_pk_mul_f32 v[30:31], v[30:31], v[102:103]
	v_pk_mul_f32 v[26:27], v[26:27], v[106:107]
	v_pk_mul_f32 v[22:23], v[22:23], v[110:111]
	v_pk_mul_f32 v[32:33], v[32:33], v[104:105]
	v_pk_mul_f32 v[28:29], v[28:29], v[108:109]
	v_pk_mul_f32 v[24:25], v[24:25], v[112:113]
	v_pk_mul_f32 v[20:21], v[20:21], v[136:137]
	v_pk_mul_f32 v[18:19], v[18:19], v[134:135]
	v_pk_mul_f32 v[62:63], v[62:63], v[102:103]
	v_pk_mul_f32 v[58:59], v[58:59], v[106:107]
	v_pk_mul_f32 v[54:55], v[54:55], v[110:111]
	v_pk_mul_f32 v[64:65], v[64:65], v[104:105]
	v_pk_mul_f32 v[60:61], v[60:61], v[108:109]
	v_pk_mul_f32 v[56:57], v[56:57], v[112:113]
	v_pk_mul_f32 v[52:53], v[52:53], v[136:137]
	v_pk_mul_f32 v[50:51], v[50:51], v[134:135]
	v_pk_mul_f32 v[46:47], v[46:47], v[102:103]
	v_pk_mul_f32 v[42:43], v[42:43], v[106:107]
	v_pk_mul_f32 v[38:39], v[38:39], v[110:111]
	v_pk_mul_f32 v[48:49], v[48:49], v[104:105]
	v_pk_mul_f32 v[44:45], v[44:45], v[108:109]
	v_pk_mul_f32 v[40:41], v[40:41], v[112:113]
	v_pk_mul_f32 v[36:37], v[36:37], v[136:137]
	v_pk_mul_f32 v[34:35], v[34:35], v[134:135]
	v_pk_mul_f32 v[14:15], v[14:15], v[102:103]
	v_pk_mul_f32 v[10:11], v[10:11], v[106:107]
	v_pk_mul_f32 v[6:7], v[6:7], v[110:111]
	v_pk_mul_f32 v[16:17], v[16:17], v[104:105]
	v_pk_mul_f32 v[12:13], v[12:13], v[108:109]
	v_pk_mul_f32 v[8:9], v[8:9], v[112:113]
	v_pk_mul_f32 v[4:5], v[4:5], v[136:137]
	v_pk_mul_f32 v[2:3], v[2:3], v[134:135]
